# phase 0 mod_item GEMV: w_ada row loads software-pipelined one K iteration ahead via shadow registers
# speedup vs baseline: 1.0146x; 1.0032x over previous
; DI void mod_item(const P& p, int item, char* lds) {
;     ...
;   const float* W = p.w_ada + (size_t)l * 1024 * 3072 + n;
;   float acc[17];
; #pragma unroll
;   for (int r = 0; r < 17; ++r) acc[r] = 0.f;
;   for (int k = ks * 64; k < ks * 64 + 64; k += 8) {
;     float wv[8];
; #pragma unroll
;     for (int u = 0; u < 8; ++u) wv[u] = W[(size_t)(k + u) * 3072];
; #pragma unroll
;     for (int u = 0; u < 8; ++u)
; #pragma unroll
;       for (int r = 0; r < 17; ++r) acc[r] += sv[r * 1024 + k + u] * wv[u];
;   }
.LBB0_971:
	s_or_b64 exec, exec, s[0:1]
	s_mul_hi_i32 s0, s23, 0x2aaaaaab
	v_lshlrev_b32_e32 v0, 1, v2
	v_lshlrev_b32_e32 v4, 3, v2
	s_lshr_b32 s1, s0, 31
	s_ashr_i32 s2, s0, 4
	v_and_b32_e32 v0, 0xffffffc0, v0
	v_and_b32_e32 v4, 0xffffff00, v4
	s_add_i32 s2, s2, s1
	v_and_b32_e32 v3, 31, v2
	v_or_b32_e32 v33, 56, v0
	v_add_u32_e32 v35, -8, v0
	v_add_u32_e32 v36, 32, v4
	v_mad_i64_i32 v[4:5], s[0:1], v0, s29, 0
	v_mov_b32_e32 v0, 0xc00000
	v_mad_i64_i32 v[4:5], s[0:1], s2, v0, v[4:5]
	v_lshl_or_b32 v0, s23, 5, v3
	s_mul_i32 s24, s2, 0xc00
	v_subrev_u32_e32 v6, s24, v0
	v_ashrrev_i32_e32 v7, 31, v6
	v_lshl_add_u64 v[4:5], v[6:7], 2, v[4:5]
	v_mov_b32_e32 v6, 0
	v_lshl_add_u64 v[4:5], s[88:89], 0, v[4:5]
	s_mov_b64 s[0:1], 0
	v_mov_b32_e32 v7, v6
	v_mov_b32_e32 v8, v6
	v_mov_b32_e32 v9, v6
	v_mov_b32_e32 v14, v6
	v_mov_b32_e32 v15, v6
	v_mov_b32_e32 v10, v6
	v_mov_b32_e32 v11, v6
	v_mov_b32_e32 v12, v6
	v_mov_b32_e32 v13, v6
	v_mov_b32_e32 v16, v6
	v_mov_b32_e32 v17, v6
	v_mov_b32_e32 v18, v6
	v_mov_b32_e32 v19, v6
	v_mov_b32_e32 v20, v6
	v_mov_b32_e32 v21, v6
	v_mov_b32_e32 v0, v6
	s_waitcnt lgkmcnt(0)
	s_barrier
	s_mov_b32 s98, 0xfffeb000
	s_mov_b32 s99, -1
	v_lshl_add_u64 v[68:69], v[4:5], 0, s[98:99]
	global_load_dword v60, v[68:69], off
	s_mov_b32 s98, 0xfffee000
	s_mov_b32 s99, -1
	v_lshl_add_u64 v[68:69], v[4:5], 0, s[98:99]
	global_load_dword v61, v[68:69], off
	s_mov_b32 s98, 0xffff1000
	s_mov_b32 s99, -1
	v_lshl_add_u64 v[68:69], v[4:5], 0, s[98:99]
	global_load_dword v62, v[68:69], off
	s_mov_b32 s98, 0xffff4000
	s_mov_b32 s99, -1
	v_lshl_add_u64 v[68:69], v[4:5], 0, s[98:99]
	global_load_dword v63, v[68:69], off
	s_mov_b32 s98, 0xffff7000
	s_mov_b32 s99, -1
	v_lshl_add_u64 v[68:69], v[4:5], 0, s[98:99]
	global_load_dword v64, v[68:69], off
	s_mov_b32 s98, 0xffffa000
	s_mov_b32 s99, -1
	v_lshl_add_u64 v[68:69], v[4:5], 0, s[98:99]
	global_load_dword v65, v[68:69], off
	s_mov_b32 s98, 0xffffd000
	s_mov_b32 s99, -1
	v_lshl_add_u64 v[68:69], v[4:5], 0, s[98:99]
	global_load_dword v66, v[68:69], off
	global_load_dword v67, v[4:5], off
	s_mov_b64 s[26:27], 0x18000
	v_lshl_add_u64 v[4:5], v[4:5], 0, s[26:27]
.LBB0_972:
	s_waitcnt vmcnt(0)
	v_mov_b32_e32 v26, v60
	v_mov_b32_e32 v27, v61
	v_mov_b32_e32 v30, v62
	v_mov_b32_e32 v31, v63
	v_mov_b32_e32 v22, v64
	v_mov_b32_e32 v23, v65
	v_mov_b32_e32 v24, v66
	v_mov_b32_e32 v25, v67
	v_add_u32_e32 v28, 0x10000, v36
	ds_read_b128 v[38:41], v28
	v_add_u32_e32 v70, 8, v35
	v_cmp_lt_i32_e32 vcc, v70, v33
	s_and_saveexec_b64 s[100:101], vcc
	s_mov_b32 s98, 0xfffeb000
	s_mov_b32 s99, -1
	v_lshl_add_u64 v[68:69], v[4:5], 0, s[98:99]
	global_load_dword v60, v[68:69], off
	s_mov_b32 s98, 0xfffee000
	s_mov_b32 s99, -1
	v_lshl_add_u64 v[68:69], v[4:5], 0, s[98:99]
	global_load_dword v61, v[68:69], off
	s_mov_b32 s98, 0xffff1000
	s_mov_b32 s99, -1
	v_lshl_add_u64 v[68:69], v[4:5], 0, s[98:99]
	global_load_dword v62, v[68:69], off
	s_mov_b32 s98, 0xffff4000
	s_mov_b32 s99, -1
	v_lshl_add_u64 v[68:69], v[4:5], 0, s[98:99]
	global_load_dword v63, v[68:69], off
	s_mov_b32 s98, 0xffff7000
	s_mov_b32 s99, -1
	v_lshl_add_u64 v[68:69], v[4:5], 0, s[98:99]
	global_load_dword v64, v[68:69], off
	s_mov_b32 s98, 0xffffa000
	s_mov_b32 s99, -1
	v_lshl_add_u64 v[68:69], v[4:5], 0, s[98:99]
	global_load_dword v65, v[68:69], off
	s_mov_b32 s98, 0xffffd000
	s_mov_b32 s99, -1
	v_lshl_add_u64 v[68:69], v[4:5], 0, s[98:99]
	global_load_dword v66, v[68:69], off
	global_load_dword v67, v[4:5], off
	s_mov_b64 s[26:27], 0x18000
	v_lshl_add_u64 v[4:5], v[4:5], 0, s[26:27]
	s_mov_b64 exec, s[100:101]
	s_waitcnt lgkmcnt(0)
	v_pk_mul_f32 v[28:29], v[26:27], v[38:39]
	s_nop 0
	v_add_f32_e32 v0, v0, v28
	v_add_f32_e32 v0, v0, v29
	v_pk_mul_f32 v[28:29], v[30:31], v[40:41]
	s_nop 0
	v_add_f32_e32 v0, v0, v28
	v_add_u32_e32 v28, 0x10010, v36
	ds_read_b128 v[38:41], v28
	v_add_f32_e32 v0, v0, v29
	s_waitcnt lgkmcnt(0)
	v_pk_mul_f32 v[28:29], v[22:23], v[38:39]
	s_nop 0
	v_add_f32_e32 v0, v0, v28
	v_add_f32_e32 v0, v0, v29
	v_mov_b32_e32 v32, v23
	v_pk_mul_f32 v[28:29], v[24:25], v[40:41]
	ds_read_b128 v[38:41], v36
	ds_read_b128 v[42:45], v36 offset:16
	ds_read_b128 v[46:49], v36 offset:4096
	v_add_f32_e32 v37, v0, v28
	v_mov_b32_e32 v0, v27
	s_waitcnt lgkmcnt(2)
	v_mov_b32_e32 v50, v38
	v_mov_b32_e32 v38, v40
	s_waitcnt lgkmcnt(0)
	v_mov_b32_e32 v51, v46
	v_mov_b32_e32 v46, v39
	v_pk_fma_f32 v[6:7], v[26:27], v[50:51], v[6:7] op_sel_hi:[0,1,1]
	v_pk_fma_f32 v[6:7], v[0:1], v[46:47], v[6:7] op_sel_hi:[0,1,1]
	v_mov_b32_e32 v39, v48
	v_mov_b32_e32 v48, v41
	v_pk_fma_f32 v[6:7], v[30:31], v[38:39], v[6:7] op_sel_hi:[0,1,1]
	ds_read_b128 v[38:41], v36 offset:4112
	v_mov_b32_e32 v28, v31
	v_pk_fma_f32 v[6:7], v[28:29], v[48:49], v[6:7] op_sel_hi:[0,1,1]
	v_mov_b32_e32 v46, v42
	v_mov_b32_e32 v34, v25
	s_waitcnt lgkmcnt(0)
	v_mov_b32_e32 v47, v38
	v_mov_b32_e32 v38, v43
	v_pk_fma_f32 v[6:7], v[22:23], v[46:47], v[6:7] op_sel_hi:[0,1,1]
	v_pk_fma_f32 v[6:7], v[32:33], v[38:39], v[6:7] op_sel_hi:[0,1,1]
	v_mov_b32_e32 v38, v44
	v_mov_b32_e32 v39, v40
	v_mov_b32_e32 v40, v45
	v_pk_fma_f32 v[6:7], v[24:25], v[38:39], v[6:7] op_sel_hi:[0,1,1]
	v_pk_fma_f32 v[6:7], v[34:35], v[40:41], v[6:7] op_sel_hi:[0,1,1]
	ds_read_b128 v[38:41], v36 offset:8192
	ds_read_b128 v[42:45], v36 offset:12288
	s_waitcnt lgkmcnt(1)
	v_mov_b32_e32 v46, v38
	s_waitcnt lgkmcnt(0)
	v_mov_b32_e32 v47, v42
	v_mov_b32_e32 v42, v39
	v_pk_fma_f32 v[8:9], v[26:27], v[46:47], v[8:9] op_sel_hi:[0,1,1]
	v_pk_fma_f32 v[8:9], v[0:1], v[42:43], v[8:9] op_sel_hi:[0,1,1]
	v_mov_b32_e32 v38, v40
	v_mov_b32_e32 v39, v44
	v_mov_b32_e32 v44, v41
	v_pk_fma_f32 v[8:9], v[30:31], v[38:39], v[8:9] op_sel_hi:[0,1,1]
	v_pk_fma_f32 v[8:9], v[28:29], v[44:45], v[8:9] op_sel_hi:[0,1,1]
	ds_read_b128 v[38:41], v36 offset:8208
	ds_read_b128 v[42:45], v36 offset:12304
	s_waitcnt lgkmcnt(1)
; DI void mod_item(const P& p, int item, char* lds) {
;     ...
;   for (int k = ks * 64; k < ks * 64 + 64; k += 8) {
;     float wv[8];
; #pragma unroll
;     for (int u = 0; u < 8; ++u) wv[u] = W[(size_t)(k + u) * 3072];
; #pragma unroll
;     for (int u = 0; u < 8; ++u)
; #pragma unroll
;       for (int r = 0; r < 17; ++r) acc[r] += sv[r * 1024 + k + u] * wv[u];
;   }
	v_mov_b32_e32 v46, v38
	s_waitcnt lgkmcnt(0)
	v_mov_b32_e32 v47, v42
	v_mov_b32_e32 v42, v39
	v_pk_fma_f32 v[8:9], v[22:23], v[46:47], v[8:9] op_sel_hi:[0,1,1]
	v_pk_fma_f32 v[8:9], v[32:33], v[42:43], v[8:9] op_sel_hi:[0,1,1]
	v_mov_b32_e32 v38, v40
	v_mov_b32_e32 v39, v44
	v_mov_b32_e32 v44, v41
	v_pk_fma_f32 v[8:9], v[24:25], v[38:39], v[8:9] op_sel_hi:[0,1,1]
	v_pk_fma_f32 v[8:9], v[34:35], v[44:45], v[8:9] op_sel_hi:[0,1,1]
	ds_read_b128 v[38:41], v36 offset:16384
	ds_read_b128 v[42:45], v36 offset:20480
	s_waitcnt lgkmcnt(1)
	v_mov_b32_e32 v46, v38
	s_waitcnt lgkmcnt(0)
	v_mov_b32_e32 v47, v42
	v_mov_b32_e32 v42, v39
	v_pk_fma_f32 v[14:15], v[26:27], v[46:47], v[14:15] op_sel_hi:[0,1,1]
	v_pk_fma_f32 v[14:15], v[0:1], v[42:43], v[14:15] op_sel_hi:[0,1,1]
	v_mov_b32_e32 v38, v40
	v_mov_b32_e32 v39, v44
	v_mov_b32_e32 v44, v41
	v_pk_fma_f32 v[14:15], v[30:31], v[38:39], v[14:15] op_sel_hi:[0,1,1]
	v_pk_fma_f32 v[14:15], v[28:29], v[44:45], v[14:15] op_sel_hi:[0,1,1]
	ds_read_b128 v[38:41], v36 offset:16400
	ds_read_b128 v[42:45], v36 offset:20496
	s_waitcnt lgkmcnt(1)
	v_mov_b32_e32 v46, v38
	s_waitcnt lgkmcnt(0)
	v_mov_b32_e32 v47, v42
	v_mov_b32_e32 v42, v39
	v_pk_fma_f32 v[14:15], v[22:23], v[46:47], v[14:15] op_sel_hi:[0,1,1]
	v_pk_fma_f32 v[14:15], v[32:33], v[42:43], v[14:15] op_sel_hi:[0,1,1]
	v_mov_b32_e32 v38, v40
	v_mov_b32_e32 v39, v44
	v_mov_b32_e32 v44, v41
	v_pk_fma_f32 v[14:15], v[24:25], v[38:39], v[14:15] op_sel_hi:[0,1,1]
	v_pk_fma_f32 v[14:15], v[34:35], v[44:45], v[14:15] op_sel_hi:[0,1,1]
	ds_read_b128 v[38:41], v36 offset:24576
	ds_read_b128 v[42:45], v36 offset:28672
	s_waitcnt lgkmcnt(1)
	v_mov_b32_e32 v46, v38
	s_waitcnt lgkmcnt(0)
	v_mov_b32_e32 v47, v42
	v_mov_b32_e32 v42, v39
	v_pk_fma_f32 v[10:11], v[26:27], v[46:47], v[10:11] op_sel_hi:[0,1,1]
	v_pk_fma_f32 v[10:11], v[0:1], v[42:43], v[10:11] op_sel_hi:[0,1,1]
	v_mov_b32_e32 v38, v40
	v_mov_b32_e32 v39, v44
	v_mov_b32_e32 v44, v41
	v_pk_fma_f32 v[10:11], v[30:31], v[38:39], v[10:11] op_sel_hi:[0,1,1]
	v_pk_fma_f32 v[10:11], v[28:29], v[44:45], v[10:11] op_sel_hi:[0,1,1]
	ds_read_b128 v[38:41], v36 offset:24592
	ds_read_b128 v[42:45], v36 offset:28688
	s_waitcnt lgkmcnt(1)
	v_mov_b32_e32 v46, v38
	s_waitcnt lgkmcnt(0)
	v_mov_b32_e32 v47, v42
	v_mov_b32_e32 v42, v39
	v_pk_fma_f32 v[10:11], v[22:23], v[46:47], v[10:11] op_sel_hi:[0,1,1]
	v_pk_fma_f32 v[10:11], v[32:33], v[42:43], v[10:11] op_sel_hi:[0,1,1]
	v_mov_b32_e32 v38, v40
	v_mov_b32_e32 v39, v44
	v_mov_b32_e32 v44, v41
	v_pk_fma_f32 v[10:11], v[24:25], v[38:39], v[10:11] op_sel_hi:[0,1,1]
	v_pk_fma_f32 v[10:11], v[34:35], v[44:45], v[10:11] op_sel_hi:[0,1,1]
	ds_read_b128 v[38:41], v36 offset:32768
	ds_read_b128 v[42:45], v36 offset:36864
	s_waitcnt lgkmcnt(1)
	v_mov_b32_e32 v46, v38
	s_waitcnt lgkmcnt(0)
	v_mov_b32_e32 v47, v42
	v_mov_b32_e32 v42, v39
	v_pk_fma_f32 v[12:13], v[26:27], v[46:47], v[12:13] op_sel_hi:[0,1,1]
	v_pk_fma_f32 v[12:13], v[0:1], v[42:43], v[12:13] op_sel_hi:[0,1,1]
	v_mov_b32_e32 v38, v40
	v_mov_b32_e32 v39, v44
	v_mov_b32_e32 v44, v41
	v_pk_fma_f32 v[12:13], v[30:31], v[38:39], v[12:13] op_sel_hi:[0,1,1]
	v_pk_fma_f32 v[12:13], v[28:29], v[44:45], v[12:13] op_sel_hi:[0,1,1]
	ds_read_b128 v[38:41], v36 offset:32784
	ds_read_b128 v[42:45], v36 offset:36880
	s_waitcnt lgkmcnt(1)
	v_mov_b32_e32 v46, v38
	s_waitcnt lgkmcnt(0)
	v_mov_b32_e32 v47, v42
	v_mov_b32_e32 v42, v39
	v_pk_fma_f32 v[12:13], v[22:23], v[46:47], v[12:13] op_sel_hi:[0,1,1]
	v_pk_fma_f32 v[12:13], v[32:33], v[42:43], v[12:13] op_sel_hi:[0,1,1]
	v_mov_b32_e32 v38, v40
	v_mov_b32_e32 v39, v44
	v_mov_b32_e32 v44, v41
	v_pk_fma_f32 v[12:13], v[24:25], v[38:39], v[12:13] op_sel_hi:[0,1,1]
	v_pk_fma_f32 v[12:13], v[34:35], v[44:45], v[12:13] op_sel_hi:[0,1,1]
	ds_read_b128 v[38:41], v36 offset:40960
	ds_read_b128 v[42:45], v36 offset:45056
	s_waitcnt lgkmcnt(1)
	v_mov_b32_e32 v46, v38
	s_waitcnt lgkmcnt(0)
	v_mov_b32_e32 v47, v42
	v_mov_b32_e32 v42, v39
	v_pk_fma_f32 v[16:17], v[26:27], v[46:47], v[16:17] op_sel_hi:[0,1,1]
	v_pk_fma_f32 v[16:17], v[0:1], v[42:43], v[16:17] op_sel_hi:[0,1,1]
	v_mov_b32_e32 v38, v40
	v_mov_b32_e32 v39, v44
	v_mov_b32_e32 v44, v41
	v_pk_fma_f32 v[16:17], v[30:31], v[38:39], v[16:17] op_sel_hi:[0,1,1]
	v_pk_fma_f32 v[16:17], v[28:29], v[44:45], v[16:17] op_sel_hi:[0,1,1]
	ds_read_b128 v[38:41], v36 offset:40976
	ds_read_b128 v[42:45], v36 offset:45072
	s_waitcnt lgkmcnt(1)
	v_mov_b32_e32 v46, v38
	s_waitcnt lgkmcnt(0)
; DI void mod_item(const P& p, int item, char* lds) {
;     ...
;   for (int k = ks * 64; k < ks * 64 + 64; k += 8) {
;     float wv[8];
; #pragma unroll
;     for (int u = 0; u < 8; ++u) wv[u] = W[(size_t)(k + u) * 3072];
; #pragma unroll
;     for (int u = 0; u < 8; ++u)
; #pragma unroll
;       for (int r = 0; r < 17; ++r) acc[r] += sv[r * 1024 + k + u] * wv[u];
;   }
; #pragma unroll
;   for (int r = 0; r < 17; ++r) acc[r] += __shfl_xor(acc[r], 32);
;   __syncthreads();
;   float* red = (float*)lds;
;   if (lane < 32) {
; #pragma unroll
;     for (int r = 0; r < 17; ++r) red[(w * 17 + r) * 32 + c] = acc[r];
	v_mov_b32_e32 v47, v42
	v_mov_b32_e32 v42, v39
	v_pk_fma_f32 v[16:17], v[22:23], v[46:47], v[16:17] op_sel_hi:[0,1,1]
	v_pk_fma_f32 v[16:17], v[32:33], v[42:43], v[16:17] op_sel_hi:[0,1,1]
	v_mov_b32_e32 v38, v40
	v_mov_b32_e32 v39, v44
	v_mov_b32_e32 v44, v41
	v_pk_fma_f32 v[16:17], v[24:25], v[38:39], v[16:17] op_sel_hi:[0,1,1]
	v_pk_fma_f32 v[16:17], v[34:35], v[44:45], v[16:17] op_sel_hi:[0,1,1]
	ds_read_b128 v[38:41], v36 offset:49152
	ds_read_b128 v[42:45], v36 offset:53248
	s_waitcnt lgkmcnt(1)
	v_mov_b32_e32 v46, v38
	s_waitcnt lgkmcnt(0)
	v_mov_b32_e32 v47, v42
	v_mov_b32_e32 v42, v39
	v_pk_fma_f32 v[18:19], v[26:27], v[46:47], v[18:19] op_sel_hi:[0,1,1]
	v_pk_fma_f32 v[18:19], v[0:1], v[42:43], v[18:19] op_sel_hi:[0,1,1]
	v_mov_b32_e32 v38, v40
	v_mov_b32_e32 v39, v44
	v_mov_b32_e32 v44, v41
	v_pk_fma_f32 v[18:19], v[30:31], v[38:39], v[18:19] op_sel_hi:[0,1,1]
	v_pk_fma_f32 v[18:19], v[28:29], v[44:45], v[18:19] op_sel_hi:[0,1,1]
	ds_read_b128 v[38:41], v36 offset:49168
	ds_read_b128 v[42:45], v36 offset:53264
	s_waitcnt lgkmcnt(1)
	v_mov_b32_e32 v46, v38
	s_waitcnt lgkmcnt(0)
	v_mov_b32_e32 v47, v42
	v_mov_b32_e32 v42, v39
	v_pk_fma_f32 v[18:19], v[22:23], v[46:47], v[18:19] op_sel_hi:[0,1,1]
	v_pk_fma_f32 v[18:19], v[32:33], v[42:43], v[18:19] op_sel_hi:[0,1,1]
	v_mov_b32_e32 v38, v40
	v_mov_b32_e32 v39, v44
	v_mov_b32_e32 v44, v41
	v_pk_fma_f32 v[18:19], v[24:25], v[38:39], v[18:19] op_sel_hi:[0,1,1]
	v_pk_fma_f32 v[18:19], v[34:35], v[44:45], v[18:19] op_sel_hi:[0,1,1]
	ds_read_b128 v[38:41], v36 offset:57344
	ds_read_b128 v[42:45], v36 offset:61440
	s_waitcnt lgkmcnt(1)
	v_mov_b32_e32 v46, v38
	s_waitcnt lgkmcnt(0)
	v_mov_b32_e32 v47, v42
	v_mov_b32_e32 v42, v39
	v_pk_fma_f32 v[20:21], v[26:27], v[46:47], v[20:21] op_sel_hi:[0,1,1]
	v_pk_fma_f32 v[20:21], v[0:1], v[42:43], v[20:21] op_sel_hi:[0,1,1]
	v_mov_b32_e32 v26, v40
	v_mov_b32_e32 v27, v44
	v_mov_b32_e32 v44, v41
	v_pk_fma_f32 v[20:21], v[30:31], v[26:27], v[20:21] op_sel_hi:[0,1,1]
	v_pk_fma_f32 v[20:21], v[28:29], v[44:45], v[20:21] op_sel_hi:[0,1,1]
	ds_read_b128 v[38:41], v36 offset:57360
	ds_read_b128 v[42:45], v36 offset:61456
	v_add_f32_e32 v0, v37, v29
	v_add_u32_e32 v36, 32, v36
	s_waitcnt lgkmcnt(1)
	v_mov_b32_e32 v26, v38
	s_waitcnt lgkmcnt(0)
	v_mov_b32_e32 v27, v42
	v_mov_b32_e32 v42, v39
	v_pk_fma_f32 v[20:21], v[22:23], v[26:27], v[20:21] op_sel_hi:[0,1,1]
	v_pk_fma_f32 v[20:21], v[32:33], v[42:43], v[20:21] op_sel_hi:[0,1,1]
	v_mov_b32_e32 v22, v40
	v_mov_b32_e32 v23, v44
	v_mov_b32_e32 v44, v41
	v_pk_fma_f32 v[20:21], v[24:25], v[22:23], v[20:21] op_sel_hi:[0,1,1]
	v_pk_fma_f32 v[20:21], v[34:35], v[44:45], v[20:21] op_sel_hi:[0,1,1]
	v_add_u32_e32 v35, 8, v35
	v_cmp_ge_i32_e32 vcc, v35, v33
	s_or_b64 s[0:1], vcc, s[0:1]
	s_andn2_b64 exec, exec, s[0:1]
	s_cbranch_execnz .LBB0_972
	s_or_b64 exec, exec, s[0:1]
	v_and_b32_e32 v5, 64, v226
	v_xor_b32_e32 v4, 32, v226
	v_add_u32_e32 v5, 64, v5
	v_cmp_lt_i32_e32 vcc, v4, v5
	v_and_b32_e32 v37, 32, v2
	s_nop 0
	v_cndmask_b32_e32 v4, v226, v4, vcc
	v_lshlrev_b32_e32 v36, 2, v4
	ds_bpermute_b32 v4, v36, v6
	ds_bpermute_b32 v5, v36, v7
	ds_bpermute_b32 v22, v36, v8
	ds_bpermute_b32 v23, v36, v9
	ds_bpermute_b32 v24, v36, v14
	ds_bpermute_b32 v25, v36, v15
	ds_bpermute_b32 v26, v36, v10
	ds_bpermute_b32 v27, v36, v11
	ds_bpermute_b32 v28, v36, v12
	ds_bpermute_b32 v29, v36, v13
	ds_bpermute_b32 v30, v36, v16
	ds_bpermute_b32 v31, v36, v17
	ds_bpermute_b32 v32, v36, v18
	ds_bpermute_b32 v33, v36, v19
	ds_bpermute_b32 v34, v36, v20
	ds_bpermute_b32 v35, v36, v21
	ds_bpermute_b32 v36, v36, v0
	v_cmp_eq_u32_e32 vcc, 0, v37
	s_barrier
	s_waitcnt lgkmcnt(0)
	s_and_saveexec_b64 s[0:1], vcc
	s_cbranch_execz .LBB0_975
	v_lshrrev_b32_e32 v37, 6, v2
	s_movk_i32 s25, 0x880
	v_add_f32_e32 v5, v7, v5
	v_add_f32_e32 v4, v6, v4
	v_lshlrev_b32_e32 v6, 2, v3
	v_mul_lo_u32 v7, v37, s25
	v_add3_u32 v6, 32, v6, v7
	v_add_f32_e32 v13, v13, v29
	v_add_f32_e32 v12, v12, v28
	v_add_f32_e32 v11, v11, v27
	v_add_f32_e32 v10, v10, v26
	v_add_f32_e32 v15, v15, v25
	v_add_f32_e32 v14, v14, v24
	v_add_f32_e32 v9, v9, v23
	v_add_f32_e32 v8, v8, v22
	ds_write2_b32 v6, v4, v5 offset1:32
	ds_write2_b32 v6, v8, v9 offset0:64 offset1:96
	ds_write2_b32 v6, v14, v15 offset0:128 offset1:160
	ds_write2_b32 v6, v10, v11 offset0:192 offset1:224
	v_add_u32_e32 v4, 0x400, v6
	v_add_f32_e32 v0, v0, v36
	v_add_f32_e32 v21, v21, v35
	v_add_f32_e32 v20, v20, v34
	v_add_f32_e32 v19, v19, v33
	v_add_f32_e32 v18, v18, v32
	v_add_f32_e32 v17, v17, v31
	v_add_f32_e32 v16, v16, v30
	ds_write2_b32 v4, v12, v13 offset1:32
	ds_write2_b32 v4, v16, v17 offset0:64 offset1:96
	ds_write2_b32 v4, v18, v19 offset0:128 offset1:160
	ds_write2_b32 v4, v20, v21 offset0:192 offset1:224
	ds_write_b32 v6, v0 offset:2048
